# stack27: SSD intra-chunk score ladder double-buffers its LDS fragment reads (on top of stack26)
# speedup vs baseline: 1.0074x; 1.0007x over previous
; DI int crow(int r, int h) { return (r & 3) + 8 * (r >> 2) + 4 * h; }
; #define MFMA32(a, b, c) __builtin_amdgcn_mfma_f32_32x32x16_bf16((a), (b), (c), 0, 0, 0)
; DI void ssd_out_unit(const Params& P, int layer, int b, int c, char* lds, int tid) {
;     ...
;         for (int sbk = 0; sbk <= lb; ++sbk) {
;             f32x16 X = {};
; #pragma unroll
;             for (int ks = 0; ks < 8; ++ks) { const bf16x8 a = *(const bf16x8*)(BM + (32 * sbk + r) * SP + 16 * ks + 8 * hh); const bf16x8 bb = *(const bf16x8*)(CM + (32 * lb + r) * SP + 16 * ks + 8 * hh);
;                 X = MFMA32(a, bb, X); }
;             f32x16 X0, X1;
; #pragma unroll
;             for (int i = 0; i < 16; ++i) { const int s = 32 * sbk + crow(i, hh); const bool vis = (s <= 32 * lb + r);
;                 X0[i] = vis ? X[i] * __expf(al0 - ac0[s]) : 0.f; X1[i] = vis ? X[i] * __expf(al1 - ac1[s]) : 0.f; }
.LBB0_372:
	v_add_u32_e32 v236, 0, v136
	v_add_u32_e32 v236, 0x22020, v236
	ds_read_b128 v[216:219], v236
	ds_read_b128 v[220:223], v236 offset:32
	ds_read_b128 v[224:227], v236 offset:64
	ds_read_b128 v[228:231], v236 offset:96
	ds_read_b128 v[232:235], v236 offset:512
	ds_read_b128 v[244:247], v236 offset:544
	ds_read_b128 v[248:251], v236 offset:576
	ds_read_b128 v[252:255], v236 offset:608
	v_add_u32_e32 v141, 0, v139
	ds_read_b128 v[34:37], v141
	ds_read_b128 v[38:41], v151
	ds_read_b128 v[174:177], v141 offset:32
	ds_read_b128 v[190:193], v151 offset:32
	v_add_u32_e32 v143, 0, v136
	v_mov_b32_e32 v142, 0
	s_waitcnt lgkmcnt(2)
	v_mfma_f32_32x32x16_bf16 v[34:49], v[34:37], v[38:41], 0
	ds_read_b128 v[194:197], v141 offset:64
	ds_read_b128 v[212:215], v151 offset:64
	s_waitcnt lgkmcnt(2)
	v_mfma_f32_32x32x16_bf16 v[34:49], v[174:177], v[190:193], v[34:49]
	ds_read_b128 v[174:177], v141 offset:96
	ds_read_b128 v[190:193], v151 offset:96
	s_waitcnt lgkmcnt(2)
	v_mfma_f32_32x32x16_bf16 v[34:49], v[194:197], v[212:215], v[34:49]
	ds_read_b128 v[194:197], v141 offset:128
	ds_read_b128 v[212:215], v151 offset:128
	s_waitcnt lgkmcnt(2)
	v_mfma_f32_32x32x16_bf16 v[34:49], v[174:177], v[190:193], v[34:49]
	ds_read_b128 v[174:177], v141 offset:160
	ds_read_b128 v[190:193], v151 offset:160
	s_waitcnt lgkmcnt(2)
	v_mfma_f32_32x32x16_bf16 v[34:49], v[194:197], v[212:215], v[34:49]
	ds_read_b128 v[194:197], v141 offset:192
	ds_read_b128 v[212:215], v151 offset:192
	s_waitcnt lgkmcnt(2)
	v_mfma_f32_32x32x16_bf16 v[34:49], v[174:177], v[190:193], v[34:49]
	ds_read_b128 v[174:177], v141 offset:224
	ds_read_b128 v[190:193], v151 offset:224
	v_mov_b32_e32 v141, 0
	s_waitcnt lgkmcnt(2)
	v_mfma_f32_32x32x16_bf16 v[34:49], v[194:197], v[212:215], v[34:49]
	s_waitcnt lgkmcnt(0)
	v_mfma_f32_32x32x16_bf16 v[34:49], v[174:177], v[190:193], v[34:49]
	s_waitcnt lgkmcnt(0)
; DI int crow(int r, int h) { return (r & 3) + 8 * (r >> 2) + 4 * h; }
; DI void ssd_out_unit(const Params& P, int layer, int b, int c, char* lds, int tid) {
;     ...
;             f32x16 X0, X1;
; #pragma unroll
;             for (int i = 0; i < 16; ++i) { const int s = 32 * sbk + crow(i, hh); const bool vis = (s <= 32 * lb + r);
;                 X0[i] = vis ? X[i] * __expf(al0 - ac0[s]) : 0.f; X1[i] = vis ? X[i] * __expf(al1 - ac1[s]) : 0.f; }
	v_sub_u32_e32 v237, v149, v138
	v_add_u32_e32 v237, 27, v237
	v_sub_f32_e32 v216, v134, v216
	v_sub_f32_e32 v232, v135, v232
	v_sub_f32_e32 v217, v134, v217
	v_sub_f32_e32 v233, v135, v233
	v_sub_f32_e32 v218, v134, v218
	v_sub_f32_e32 v234, v135, v234
	v_sub_f32_e32 v219, v134, v219
	v_sub_f32_e32 v235, v135, v235
	v_sub_f32_e32 v220, v134, v220
	v_sub_f32_e32 v244, v135, v244
	v_sub_f32_e32 v221, v134, v221
	v_sub_f32_e32 v245, v135, v245
	v_sub_f32_e32 v222, v134, v222
	v_sub_f32_e32 v246, v135, v246
	v_sub_f32_e32 v223, v134, v223
	v_sub_f32_e32 v247, v135, v247
	v_sub_f32_e32 v224, v134, v224
	v_sub_f32_e32 v248, v135, v248
	v_sub_f32_e32 v225, v134, v225
	v_sub_f32_e32 v249, v135, v249
	v_sub_f32_e32 v226, v134, v226
	v_sub_f32_e32 v250, v135, v250
	v_sub_f32_e32 v227, v134, v227
	v_sub_f32_e32 v251, v135, v251
	v_sub_f32_e32 v228, v134, v228
	v_sub_f32_e32 v252, v135, v252
	v_sub_f32_e32 v229, v134, v229
	v_sub_f32_e32 v253, v135, v253
	v_sub_f32_e32 v230, v134, v230
	v_sub_f32_e32 v254, v135, v254
	v_sub_f32_e32 v231, v134, v231
	v_sub_f32_e32 v255, v135, v255
	v_mul_f32_e32 v216, 0x3fb8aa3b, v216
	v_mul_f32_e32 v232, 0x3fb8aa3b, v232
	v_mul_f32_e32 v217, 0x3fb8aa3b, v217
	v_mul_f32_e32 v233, 0x3fb8aa3b, v233
	v_mul_f32_e32 v218, 0x3fb8aa3b, v218
	v_mul_f32_e32 v234, 0x3fb8aa3b, v234
	v_mul_f32_e32 v219, 0x3fb8aa3b, v219
	v_mul_f32_e32 v235, 0x3fb8aa3b, v235
	v_mul_f32_e32 v220, 0x3fb8aa3b, v220
	v_mul_f32_e32 v244, 0x3fb8aa3b, v244
	v_mul_f32_e32 v221, 0x3fb8aa3b, v221
	v_mul_f32_e32 v245, 0x3fb8aa3b, v245
	v_mul_f32_e32 v222, 0x3fb8aa3b, v222
	v_mul_f32_e32 v246, 0x3fb8aa3b, v246
	v_mul_f32_e32 v223, 0x3fb8aa3b, v223
	v_mul_f32_e32 v247, 0x3fb8aa3b, v247
	v_mul_f32_e32 v224, 0x3fb8aa3b, v224
	v_mul_f32_e32 v248, 0x3fb8aa3b, v248
	v_mul_f32_e32 v225, 0x3fb8aa3b, v225
	v_mul_f32_e32 v249, 0x3fb8aa3b, v249
	v_mul_f32_e32 v226, 0x3fb8aa3b, v226
	v_mul_f32_e32 v250, 0x3fb8aa3b, v250
	v_mul_f32_e32 v227, 0x3fb8aa3b, v227
	v_mul_f32_e32 v251, 0x3fb8aa3b, v251
	v_mul_f32_e32 v228, 0x3fb8aa3b, v228
	v_mul_f32_e32 v252, 0x3fb8aa3b, v252
	v_mul_f32_e32 v229, 0x3fb8aa3b, v229
	v_mul_f32_e32 v253, 0x3fb8aa3b, v253
	v_mul_f32_e32 v230, 0x3fb8aa3b, v230
	v_mul_f32_e32 v254, 0x3fb8aa3b, v254
	v_mul_f32_e32 v231, 0x3fb8aa3b, v231
	v_mul_f32_e32 v255, 0x3fb8aa3b, v255
	v_exp_f32_e32 v216, v216
	v_exp_f32_e32 v232, v232
	v_exp_f32_e32 v217, v217
	v_exp_f32_e32 v233, v233
	v_exp_f32_e32 v218, v218
	v_exp_f32_e32 v234, v234
	v_exp_f32_e32 v219, v219
	v_exp_f32_e32 v235, v235
	v_exp_f32_e32 v220, v220
	v_exp_f32_e32 v244, v244
	v_exp_f32_e32 v221, v221
	v_exp_f32_e32 v245, v245
	v_exp_f32_e32 v222, v222
	v_exp_f32_e32 v246, v246
	v_exp_f32_e32 v223, v223
	v_exp_f32_e32 v247, v247
	v_exp_f32_e32 v224, v224
	v_exp_f32_e32 v248, v248
	v_exp_f32_e32 v225, v225
	v_exp_f32_e32 v249, v249
	v_exp_f32_e32 v226, v226
	v_exp_f32_e32 v250, v250
	v_exp_f32_e32 v227, v227
	v_exp_f32_e32 v251, v251
	v_exp_f32_e32 v228, v228
	v_exp_f32_e32 v252, v252
	v_exp_f32_e32 v229, v229
	v_exp_f32_e32 v253, v253
	v_exp_f32_e32 v230, v230
	v_exp_f32_e32 v254, v254
	v_exp_f32_e32 v231, v231
	v_exp_f32_e32 v255, v255
	s_nop 0
	v_mul_f32_e32 v216, v34, v216
	v_mul_f32_e32 v232, v34, v232
	v_mul_f32_e32 v217, v35, v217
	v_mul_f32_e32 v233, v35, v233
	v_mul_f32_e32 v218, v36, v218
	v_mul_f32_e32 v234, v36, v234
	v_mul_f32_e32 v219, v37, v219
	v_mul_f32_e32 v235, v37, v235
	v_mul_f32_e32 v220, v38, v220
	v_mul_f32_e32 v244, v38, v244
	v_mul_f32_e32 v221, v39, v221
	v_mul_f32_e32 v245, v39, v245
	v_mul_f32_e32 v222, v40, v222
	v_mul_f32_e32 v246, v40, v246
	v_mul_f32_e32 v223, v41, v223
	v_mul_f32_e32 v247, v41, v247
	v_mul_f32_e32 v224, v42, v224
	v_mul_f32_e32 v248, v42, v248
	v_mul_f32_e32 v225, v43, v225
	v_mul_f32_e32 v249, v43, v249
	v_mul_f32_e32 v226, v44, v226
	v_mul_f32_e32 v250, v44, v250
	v_mul_f32_e32 v227, v45, v227
	v_mul_f32_e32 v251, v45, v251
	v_mul_f32_e32 v228, v46, v228
	v_mul_f32_e32 v252, v46, v252
	v_mul_f32_e32 v229, v47, v229
	v_mul_f32_e32 v253, v47, v253
	v_mul_f32_e32 v230, v48, v230
	v_mul_f32_e32 v254, v48, v254
	v_mul_f32_e32 v231, v49, v231
	v_mul_f32_e32 v255, v49, v255
	v_cmp_le_i32_e32 vcc, 0, v237
	s_nop 1
	v_cndmask_b32_e32 v142, 0, v216, vcc
	v_cndmask_b32_e32 v174, 0, v232, vcc
	v_cmp_le_i32_e32 vcc, 1, v237
	s_nop 1
	v_cndmask_b32_e32 v141, 0, v217, vcc
	v_cndmask_b32_e32 v34, 0, v233, vcc
	v_cmp_le_i32_e32 vcc, 2, v237
	s_nop 1
	v_cndmask_b32_e32 v175, 0, v218, vcc
	v_cndmask_b32_e32 v35, 0, v234, vcc
	v_cmp_le_i32_e32 vcc, 3, v237
	s_nop 1
	v_cndmask_b32_e32 v176, 0, v219, vcc
	v_cndmask_b32_e32 v36, 0, v235, vcc
	v_cmp_le_i32_e32 vcc, 8, v237
	s_nop 1
	v_cndmask_b32_e32 v177, 0, v220, vcc
	v_cndmask_b32_e32 v37, 0, v244, vcc
	v_cmp_le_i32_e32 vcc, 9, v237
	s_nop 1
	v_cndmask_b32_e32 v190, 0, v221, vcc
	v_cndmask_b32_e32 v38, 0, v245, vcc
	v_cmp_le_i32_e32 vcc, 10, v237
	s_nop 1
	v_cndmask_b32_e32 v191, 0, v222, vcc
	v_cndmask_b32_e32 v39, 0, v246, vcc
	v_cmp_le_i32_e32 vcc, 11, v237
	s_nop 1
	v_cndmask_b32_e32 v192, 0, v223, vcc
	v_cndmask_b32_e32 v193, 0, v247, vcc
	v_cmp_le_i32_e32 vcc, 16, v237
	s_nop 1
	v_cndmask_b32_e32 v40, 0, v224, vcc
	v_cndmask_b32_e32 v41, 0, v248, vcc
	v_cmp_le_i32_e32 vcc, 17, v237
	s_nop 1
	v_cndmask_b32_e32 v194, 0, v225, vcc
	v_cndmask_b32_e32 v42, 0, v249, vcc
	v_cmp_le_i32_e32 vcc, 18, v237
	s_nop 1
	v_cndmask_b32_e32 v195, 0, v226, vcc
	v_cndmask_b32_e32 v43, 0, v250, vcc
	v_cmp_le_i32_e32 vcc, 19, v237
	s_nop 1
	v_cndmask_b32_e32 v196, 0, v227, vcc
	v_cndmask_b32_e32 v44, 0, v251, vcc
	v_cmp_le_i32_e32 vcc, 24, v237
	s_nop 1
	v_cndmask_b32_e32 v197, 0, v228, vcc
	v_cndmask_b32_e32 v45, 0, v252, vcc
	v_cmp_le_i32_e32 vcc, 25, v237
	s_nop 1
	v_cndmask_b32_e32 v198, 0, v229, vcc
	v_cndmask_b32_e32 v46, 0, v253, vcc
	v_cmp_le_i32_e32 vcc, 26, v237
	s_nop 1
	v_cndmask_b32_e32 v199, 0, v230, vcc
	v_cndmask_b32_e32 v47, 0, v254, vcc
	v_cmp_le_i32_e32 vcc, 27, v237
	s_nop 1
	v_cndmask_b32_e32 v200, 0, v231, vcc
	v_cndmask_b32_e32 v48, 0, v255, vcc
	s_branch .LBB0_371
